# odd teams: layer-0 down / next norm1 / in-proj software-pipelined over the two panels (in-proj half mode), so both norm1 halves fall into other teams' GEMM time
# baseline (speedup 1.0000x reference)
.LBB0_15:
	v_readlane_b32 s2, v255, 48
	s_cmp_eq_u32 s2, 0
	s_cbranch_scc1 .Lsq_std
	s_cmp_eq_u32 s2, 1
	s_cbranch_scc0 .Lsq_m2
	s_mov_b32 s3, 0x48240
	s_bitcmp1_b32 s3, s80
	s_cbranch_scc0 .Lsq_back
	s_add_i32 s80, s80, 1
	s_mov_b64 s[0:1], -1
	s_branch .LBB0_423
.Lsq_back:
	s_add_i32 s80, s80, -1
	s_mov_b32 s2, 2
	v_writelane_b32 v255, s2, 48
	s_barrier
	s_mov_b64 s[0:1], 0
	s_branch .LBB0_477
.Lsq_m2:
	s_mov_b32 s3, 0x90880
	s_bitcmp1_b32 s3, s80
	s_cbranch_scc1 .Lsq_std
	s_add_i32 s6, s80, 1
	s_bitcmp1_b32 s3, s6
	s_cbranch_scc1 .Lsq_last
	s_add_i32 s80, s80, 2
	s_mov_b32 s2, 1
	v_writelane_b32 v255, s2, 48
	s_mov_b64 s[0:1], -1
	s_branch .LBB0_423
.Lsq_last:
	s_add_i32 s80, s80, 1
	s_mov_b64 s[0:1], -1
	s_branch .LBB0_423

.LBB0_319:
	s_andn2_b64 vcc, exec, s[0:1]
	s_cbranch_vccnz .LBB0_411
	v_readlane_b32 s0, v255, 35
	s_cmp_gt_i32 s0, 0
	s_mov_b64 s[0:1], -1
	s_cbranch_scc0 .LBB0_380
	v_readlane_b32 s0, v253, 58
	s_waitcnt vmcnt(0)
	v_mov_b32_e32 v12, v200
	v_readlane_b32 s1, v253, 59
	s_andn2_b64 vcc, exec, s[0:1]
	v_readfirstlane_b32 s0, v12
	s_cbranch_vccnz .LBB0_379
	v_lshlrev_b32_e32 v0, 4, v12
	v_add_u32_e32 v1, 0x2000, v0
	v_ashrrev_i32_e32 v2, 31, v1
	v_lshrrev_b32_e32 v2, 22, v2
	v_add_u32_e32 v2, v1, v2
	v_ashrrev_i32_e32 v2, 10, v2
	v_mul_i32_i24_e32 v3, 0x400, v2
	v_sub_u32_e32 v1, v1, v3
	v_lshrrev_b32_e32 v3, 4, v1
	v_bitop3_b32 v1, v3, v1, 32 bitop3:0x6c
	v_ashrrev_i32_e32 v3, 31, v1
	v_lshrrev_b32_e32 v3, 26, v3
	v_readlane_b32 s2, v255, 23
	v_readlane_b32 s12, v255, 31
	v_add_u32_e32 v3, v1, v3
	v_lshlrev_b32_e32 v5, 3, v2
	s_ashr_i32 s1, s0, 6
	v_readlane_b32 s3, v255, 24
	s_mov_b32 s20, s2
	s_ashr_i32 s21, s2, 31
	v_readlane_b32 s13, v255, 32
	v_ashrrev_i32_e32 v4, 6, v3
	v_and_b32_e32 v5, -16, v5
	v_lshlrev_b32_e32 v2, 5, v2
	s_ashr_i32 s14, s0, 8
	s_lshl_b64 s[2:3], s[20:21], 8
	s_lshl_b64 s[6:7], s[20:21], 9
	s_lshl_b32 s34, s1, 10
	s_lshl_b64 s[12:13], s[12:13], 23
	v_readlane_b32 s16, v253, 43
	v_add_u32_e32 v5, v4, v5
	v_and_b32_e32 v13, 32, v2
	v_and_b32_e32 v2, 0xc0, v3
	s_add_u32 s35, s16, s12
	v_and_b32_e32 v4, 3, v4
	s_mov_b32 s12, 0x7fffffe0
	v_lshrrev_b32_e32 v6, 2, v5
	v_lshlrev_b32_e32 v7, 1, v5
	v_sub_u32_e32 v1, v1, v2
	v_and_or_b32 v4, v5, s12, v4
	v_and_b32_e32 v6, 4, v6
	v_and_b32_e32 v7, 24, v7
	v_ashrrev_i16_sdwa v1, v203, sext(v1) dst_sel:DWORD dst_unused:UNUSED_PAD src0_sel:DWORD src1_sel:BYTE_0
	v_or3_b32 v4, v4, v6, v7
	v_bfe_i32 v14, v1, 0, 16
	v_mul_lo_u32 v4, v4, s20
	v_add_u32_e32 v1, v13, v14
	v_mul_lo_u32 v15, v5, s20
	v_add_lshl_u32 v140, v4, v1, 1
	v_add_lshl_u32 v142, v1, v15, 1
	v_bfe_i32 v1, v12, 27, 1
	v_lshrrev_b32_e32 v1, 22, v1
	v_add_u32_e32 v1, v0, v1
	v_and_b32_e32 v1, 0xfffffc00, v1
	v_sub_u32_e32 v0, v0, v1
	v_ashrrev_i32_e32 v2, 31, v12
	v_lshrrev_b32_e32 v1, 4, v0
	v_lshrrev_b32_e32 v2, 26, v2
	v_bitop3_b32 v1, v1, v0, 32 bitop3:0x6c
	v_ashrrev_i32_e32 v0, 31, v0
	v_add_u32_e32 v2, v12, v2
	v_lshrrev_b32_e32 v0, 26, v0
	v_ashrrev_i32_e32 v2, 6, v2
	v_add_u32_e32 v0, v1, v0
	v_lshlrev_b32_e32 v3, 3, v2
	v_ashrrev_i32_e32 v0, 6, v0
	v_and_b32_e32 v3, -16, v3
	v_add_u32_e32 v3, v0, v3
	v_and_b32_e32 v4, 3, v0
	v_lshrrev_b32_e32 v5, 2, v3
	v_lshlrev_b32_e32 v6, 1, v3
	v_readlane_b32 s17, v253, 44
	v_and_or_b32 v4, v3, s12, v4
	v_and_b32_e32 v5, 4, v5
	v_and_b32_e32 v6, 24, v6
	v_readlane_b32 s12, v254, 57
	v_readlane_b32 s16, v254, 56
	s_addc_u32 s36, s17, s13
	v_or3_b32 v4, v4, v5, v6
	s_mul_i32 s12, s6, s12
	s_mul_hi_u32 s13, s6, s16
	v_mul_lo_u32 v4, v4, s20
	v_mul_lo_u32 v18, v3, s20
	s_add_i32 s15, s13, s12
	s_mov_b64 s[24:25], s[20:21]
	s_lshr_b64 s[12:13], s[20:21], 23
	v_readlane_b32 s20, v254, 52
	s_mul_i32 s13, s12, s16
	v_readlane_b32 s21, v254, 53
	v_mul_i32_i24_e32 v0, 64, v0
	s_add_i32 s15, s15, s13
	s_mul_i32 s13, s6, s21
	s_mul_hi_u32 s17, s6, s20
	v_sub_u32_e32 v0, v1, v0
	s_add_i32 s13, s17, s13
	s_mul_i32 s12, s12, s20
	v_lshlrev_b32_e32 v2, 5, v2
	v_ashrrev_i16_sdwa v0, v203, sext(v0) dst_sel:DWORD dst_unused:UNUSED_PAD src0_sel:DWORD src1_sel:BYTE_0
	s_add_i32 s13, s13, s12
	s_mul_i32 s12, s6, s20
	v_and_b32_e32 v16, 32, v2
	v_bfe_i32 v17, v0, 0, 16
	s_add_u32 s26, s35, s12
	v_add_u32_e32 v0, v16, v17
	s_addc_u32 s27, s36, s13
	s_add_i32 s37, s34, 16
	v_add_lshl_u32 v128, v4, v0, 1
	s_add_i32 m0, s37, 0x10000
	s_mul_i32 s16, s6, s16
	global_load_lds_dwordx4 v128, s[26:27]
	s_add_i32 m0, s37, 0x12000
	s_add_u32 s12, s26, s2
	global_load_lds_dwordx4 v140, s[26:27]
	s_addc_u32 s13, s27, s3
	s_add_i32 m0, s37, 0x14000
	s_mov_b64 s[20:21], s[38:39]
	global_load_lds_dwordx4 v128, s[12:13]
	s_add_i32 m0, s37, 0x16000
	s_add_u32 s28, s8, s16
	s_addc_u32 s29, s9, s15
	v_readlane_b32 s100, v255, 48
	s_cmp_eq_u32 s100, 2
	s_cselect_b32 s101, 0x400000, 0
	s_add_u32 s28, s28, s101
	s_addc_u32 s29, s29, 0
	s_add_i32 s38, s37, 0x2000
	v_add_lshl_u32 v144, v0, v18, 1
	global_load_lds_dwordx4 v140, s[12:13]
	s_mov_b32 m0, s37
	s_add_u32 s16, s28, s2
	global_load_lds_dwordx4 v144, s[28:29]
	s_mov_b32 m0, s38
	s_addc_u32 s17, s29, s3
	s_add_i32 s39, s37, 0x4000
	global_load_lds_dwordx4 v142, s[28:29]
	s_mov_b32 m0, s39
	s_add_i32 s42, s37, 0x6000
	global_load_lds_dwordx4 v144, s[16:17]
	s_mov_b32 m0, s42
	s_load_dword s43, s[20:21], 0x0
	global_load_lds_dwordx4 v142, s[16:17]
	v_mov_b32_e32 v141, v129
	v_mov_b32_e32 v145, v129
	v_mov_b32_e32 v143, v129
	s_cmp_eq_u32 s14, 1
	v_lshl_add_u64 v[8:9], s[26:27], 0, v[128:129]
	v_lshl_add_u64 v[4:5], s[26:27], 0, v[140:141]
	v_lshl_add_u64 v[2:3], s[12:13], 0, v[128:129]
	v_lshl_add_u64 v[0:1], s[12:13], 0, v[140:141]
	v_lshl_add_u64 v[6:7], s[28:29], 0, v[144:145]
	s_cselect_b64 s[12:13], -1, 0
	s_cmp_lg_u32 s14, 1
	v_lshl_add_u64 v[10:11], s[28:29], 0, v[142:143]
	s_cbranch_scc1 .LBB0_324
	s_barrier
.LBB0_324:
	s_add_i32 m0, s37, 0x18000
	v_lshl_add_u64 v[8:9], v[8:9], 0, s[98:99]
	s_waitcnt vmcnt(2)
	s_barrier
	global_load_lds_dwordx4 v[8:9], off
	v_lshl_add_u64 v[4:5], v[4:5], 0, s[98:99]
	s_add_i32 m0, s37, 0x1a000
	s_add_i32 s44, s37, 0x8000
	global_load_lds_dwordx4 v[4:5], off
	v_lshl_add_u64 v[4:5], v[6:7], 0, s[98:99]
	s_mov_b32 m0, s44
	s_add_i32 s45, s37, 0xa000
	global_load_lds_dwordx4 v[4:5], off
	v_lshl_add_u64 v[4:5], v[10:11], 0, s[98:99]
	s_mov_b32 m0, s45
	v_lshl_add_u64 v[2:3], v[2:3], 0, s[98:99]
	global_load_lds_dwordx4 v[4:5], off
	s_add_i32 m0, s37, 0x1c000
	v_lshl_add_u64 v[0:1], v[0:1], 0, s[98:99]
	global_load_lds_dwordx4 v[2:3], off
	s_add_i32 m0, s37, 0x1e000
	s_lshl_b32 s1, s1, 5
	global_load_lds_dwordx4 v[0:1], off
	v_lshrrev_b32_e32 v1, 1, v12
	v_and_b32_e32 v1, 24, v1
	v_and_b32_e32 v0, 15, v12
	v_lshlrev_b32_e32 v2, 1, v1
	v_lshl_or_b32 v135, s14, 6, v0
	v_lshl_or_b32 v0, v0, 6, v2
	v_lshlrev_b32_e32 v2, 2, v12
	s_lshr_b32 s15, s25, 26
	s_lshl_b32 s14, s14, 13
	v_and_b32_e32 v2, 32, v2
	s_and_b32 s1, s1, 0x60
	s_add_i32 s15, s24, s15
	v_bitop3_b32 v3, v0, s14, v2 bitop3:0xde
	s_lshl_b32 s14, s1, 7
	s_ashr_i32 s46, s15, 6
	v_bitop3_b32 v137, v0, s14, v2 bitop3:0xde
	v_add_u32_e32 v0, v18, v16
	s_cmp_gt_i32 s24, 63
	v_or_b32_e32 v154, s1, v1
	v_add_lshl_u32 v0, v0, v17, 1
	v_mov_b32_e32 v1, v129
	s_waitcnt vmcnt(6)
	s_cselect_b64 s[14:15], -1, 0
	s_add_i32 s47, s46, -2
	v_lshl_add_u64 v[146:147], s[2:3], 0, v[0:1]
	v_add_u32_e32 v0, v15, v13
	s_cmpk_lt_u32 s0, 0x100
	v_add_lshl_u32 v0, v0, v14, 1
	s_cselect_b64 s[16:17], -1, 0
	s_waitcnt lgkmcnt(0)
	s_ashr_i32 s48, s43, 31
	v_lshl_add_u64 v[148:149], s[2:3], 0, v[0:1]
	v_readlane_b32 s100, v255, 48
	s_cmp_eq_u32 s100, 2
	s_cselect_b32 s49, 4, 0
	v_add_u32_e32 v155, 16, v3
	v_readlane_b32 s52, v254, 51
	v_readlane_b32 s53, v254, 56
	s_cmp_eq_u32 s100, 2
	s_cselect_b32 s101, 8, 0
	s_add_i32 s53, s53, s101
	s_barrier
	s_branch .LBB0_327

.LBB0_327:
	s_add_i32 s49, s49, 1
	s_mul_i32 s0, s49, s48
	s_mul_hi_u32 s1, s49, s43
	s_add_i32 s1, s1, s0
	s_mul_i32 s0, s49, s43
	s_add_u32 s20, s0, s62
	s_addc_u32 s21, s1, s63
	v_mov_b64_e32 v[0:1], 0x800
	v_cmp_gt_i64_e32 vcc, s[20:21], v[138:139]
	v_cmp_lt_i64_e64 s[0:1], s[20:21], v[0:1]
	s_cbranch_vccnz .LBB0_333
	s_add_i32 s50, s52, 4
	s_mov_b32 s51, s53
	s_cmp_lt_i32 s50, 16
	s_cbranch_scc1 .Ldec_3
	s_sub_i32 s50, s50, 16
	s_add_i32 s51, s53, 8
	v_readlane_b32 s100, v255, 48
	s_cmp_eq_u32 s100, 1
	s_cbranch_scc0 .Ldec_3
	s_mov_b64 s[0:1], 0
